# v9: NSA1 q/gate prefetch + late weight conversion shared by workgroups 32..255 (without the selection rewrite)
# speedup vs baseline: 1.0574x; 1.0019x over previous
.LBB0_276:
	s_cmp_lt_i32 s28, 3
	s_cselect_b64 s[0:1], -1, 0
	s_cmp_gt_i32 s29, 2
	s_cselect_b64 s[2:3], -1, 0
	s_and_b64 s[0:1], s[0:1], s[2:3]
	s_andn2_b64 vcc, exec, s[0:1]
	s_cbranch_vccnz .LBB0_445
	s_cmpk_lt_i32 s30, 0xc0
	s_cselect_b64 s[0:1], -1, 0
	s_cmpk_lt_i32 s16, 0x20
	s_cselect_b64 s[2:3], -1, 0
	s_or_b64 s[0:1], s[2:3], s[0:1]
	v_mov_b32_e32 v0, v200
	s_and_b64 vcc, exec, s[0:1]
	s_cbranch_vccnz .LBB0_327
	v_readlane_b32 s0, v254, 3
	s_add_i32 s0, s0, 0xffffc000
	s_nop 0
	v_add_u32_e32 v4, s0, v0
	s_lshl_b32 s0, s30, 9
	s_add_i32 s8, s0, 0xffffc000
	s_movk_i32 s0, 0x3fff
	v_cmp_lt_i32_e64 s[2:3], s0, v4
	s_movk_i32 s0, 0x4000
	v_cmp_gt_i32_e32 vcc, s0, v4
	v_ashrrev_i32_e32 v5, 31, v4
	s_and_saveexec_b64 s[10:11], vcc
	s_cbranch_execz .LBB0_285
	v_lshlrev_b64 v[0:1], 11, v[4:5]
	s_ashr_i32 s9, s8, 31
	v_lshl_add_u64 v[0:1], s[26:27], 0, v[0:1]
	s_mov_b64 s[4:5], 0x400000
	v_lshl_add_u64 v[6:7], v[0:1], 0, s[4:5]
	s_lshl_b64 s[12:13], s[8:9], 11
	s_waitcnt lgkmcnt(0)
	v_lshl_add_u64 v[8:9], v[4:5], 2, s[74:75]
	s_lshl_b64 s[14:15], s[8:9], 2
	s_mov_b64 s[18:19], 0
	v_mov_b32_e32 v11, 0
	s_mov_b64 s[20:21], 0x3fff
	s_mov_b32 s4, 0
	v_mov_b64_e32 v[12:13], v[4:5]
	s_branch .LBB0_281

.LBB0_516:
	s_or_b64 exec, exec, s[2:3]
	v_ashrrev_i32_e32 v2, 1, v1
	v_bfe_u32 v4, v1, 5, 1
	v_and_b32_e32 v3, 0xffffffe0, v2
	v_bfi_b32 v2, s64, v2, v1
	v_mul_lo_u32 v95, v2, s65
	v_lshlrev_b32_e32 v2, 2, v4
	v_add3_u32 v2, 0, v95, v2
	v_cmp_lt_i32_e32 vcc, v92, v93
	v_and_b32_e32 v0, 63, v1
	v_add_u32_e32 v96, 0xd000, v2
	v_cndmask_b32_e32 v2, v91, v92, vcc
	s_and_b32 s0, s50, 0x700
	v_and_b32_e32 v64, 31, v1
	v_lshlrev_b32_e32 v97, 2, v2
	v_cmp_gt_u32_e64 s[2:3], 32, v0
	v_and_b32_e32 v0, 16, v1
	v_bfe_u32 v2, v1, 2, 2
	v_lshrrev_b32_e32 v8, 3, v1
	v_lshlrev_b32_e32 v1, 2, v1
	v_and_or_b32 v0, v1, 12, v0
	v_add_u32_e32 v10, s0, v3
	v_lshlrev_b32_e32 v9, 1, v0
	v_or_b32_e32 v0, v10, v64
	v_mad_i32_i24 v10, v4, s66, v10
	v_or_b32_e32 v10, v10, v64
	v_add_u32_e32 v11, 0xfffff832, v10
	v_med3_i32 v11, v11, 0, v90
	v_lshl_add_u32 v98, v11, 2, s69
	v_add_u32_e32 v11, 0xfffff842, v10
	v_med3_i32 v11, v11, 0, v90
	v_lshl_add_u32 v99, v11, 2, s69
	v_add_u32_e32 v11, 0xfffff852, v10
	v_med3_i32 v11, v11, 0, v90
	v_lshl_add_u32 v100, v11, 2, s69
	v_add_u32_e32 v11, 0xfffff862, v10
	v_med3_i32 v11, v11, 0, v90
	v_lshl_add_u32 v101, v11, 2, s69
	v_add_u32_e32 v11, 0xfffff8b2, v10
	v_med3_i32 v11, v11, 0, v90
	v_lshl_add_u32 v102, v11, 2, s69
	v_add_u32_e32 v11, 0xfffff8c2, v10
	v_med3_i32 v11, v11, 0, v90
	v_lshl_add_u32 v103, v11, 2, s69
	v_add_u32_e32 v11, 0xfffff8d2, v10
	v_med3_i32 v11, v11, 0, v90
	v_lshl_add_u32 v104, v11, 2, s69
	v_add_u32_e32 v11, 0xfffff8e2, v10
	v_med3_i32 v11, v11, 0, v90
	v_lshl_add_u32 v105, v11, 2, s69
	v_add_u32_e32 v11, 0xfffff932, v10
	v_med3_i32 v11, v11, 0, v90
	v_lshl_add_u32 v106, v11, 2, s69
	v_add_u32_e32 v11, 0xfffff942, v10
	v_med3_i32 v11, v11, 0, v90
	v_lshl_add_u32 v107, v11, 2, s69
	v_add_u32_e32 v11, 0xfffff952, v10
	v_med3_i32 v11, v11, 0, v90
	v_lshl_add_u32 v108, v11, 2, s69
	v_add_u32_e32 v11, 0xfffff962, v10
	v_med3_i32 v11, v11, 0, v90
	v_lshl_add_u32 v109, v11, 2, s69
	v_add_u32_e32 v11, 0xfffff9b2, v10
	v_med3_i32 v11, v11, 0, v90
	v_lshl_add_u32 v110, v11, 2, s69
	v_add_u32_e32 v11, 0xfffff9c2, v10
	v_med3_i32 v11, v11, 0, v90
	v_lshl_add_u32 v111, v11, 2, s69
	v_add_u32_e32 v11, 0xfffff9d2, v10
	v_med3_i32 v11, v11, 0, v90
	v_lshl_add_u32 v112, v11, 2, s69
	v_add_u32_e32 v11, 0xfffff9e2, v10
	v_med3_i32 v11, v11, 0, v90
	v_lshl_add_u32 v113, v11, 2, s69
	v_add_u32_e32 v11, 0xfffffa32, v10
	v_med3_i32 v11, v11, 0, v90
	v_lshl_add_u32 v114, v11, 2, s69
	v_add_u32_e32 v11, 0xfffffa42, v10
	v_med3_i32 v11, v11, 0, v90
	v_lshl_add_u32 v115, v11, 2, s69
	v_add_u32_e32 v11, 0xfffffa52, v10
	v_med3_i32 v11, v11, 0, v90
	v_lshl_add_u32 v116, v11, 2, s69
	v_add_u32_e32 v11, 0xfffffa62, v10
	v_med3_i32 v11, v11, 0, v90
	v_lshl_add_u32 v117, v11, 2, s69
	v_add_u32_e32 v11, 0xfffffab2, v10
	v_med3_i32 v11, v11, 0, v90
	v_lshl_add_u32 v118, v11, 2, s69
	v_add_u32_e32 v11, 0xfffffac2, v10
	v_med3_i32 v11, v11, 0, v90
	v_lshl_add_u32 v119, v11, 2, s69
	v_add_u32_e32 v11, 0xfffffad2, v10
	v_med3_i32 v11, v11, 0, v90
	v_lshl_add_u32 v120, v11, 2, s69
	v_add_u32_e32 v11, 0xfffffae2, v10
	v_med3_i32 v11, v11, 0, v90
	v_lshl_add_u32 v121, v11, 2, s69
	v_add_u32_e32 v11, 0xfffffb32, v10
	v_med3_i32 v11, v11, 0, v90
	v_lshl_add_u32 v122, v11, 2, s69
	v_add_u32_e32 v11, 0xfffffb42, v10
	v_med3_i32 v11, v11, 0, v90
	v_lshl_add_u32 v123, v11, 2, s69
	v_add_u32_e32 v11, 0xfffffb52, v10
	v_med3_i32 v11, v11, 0, v90
	v_lshl_add_u32 v124, v11, 2, s69
	v_add_u32_e32 v11, 0xfffffb62, v10
	v_med3_i32 v11, v11, 0, v90
	v_lshl_add_u32 v125, v11, 2, s69
	v_add_u32_e32 v11, 0xfffffbb2, v10
	v_med3_i32 v11, v11, 0, v90
	v_lshl_add_u32 v126, v11, 2, s69
	v_add_u32_e32 v11, 0xfffffbc2, v10
	v_med3_i32 v11, v11, 0, v90
	v_lshl_add_u32 v127, v11, 2, s69
	v_add_u32_e32 v11, 0xfffffbd2, v10
	v_med3_i32 v11, v11, 0, v90
	v_lshl_add_u32 v128, v11, 2, s69
	v_add_u32_e32 v11, 0xfffffbe2, v10
	v_med3_i32 v11, v11, 0, v90
	v_lshl_add_u32 v129, v11, 2, s69
	v_add_u32_e32 v11, 0xfffffc32, v10
	v_med3_i32 v11, v11, 0, v90
	v_lshl_add_u32 v130, v11, 2, s69
	v_add_u32_e32 v11, 0xfffffc42, v10
	v_med3_i32 v11, v11, 0, v90
	v_lshl_add_u32 v131, v11, 2, s69
	v_add_u32_e32 v11, 0xfffffc52, v10
	v_med3_i32 v11, v11, 0, v90
	v_lshl_add_u32 v132, v11, 2, s69
	v_add_u32_e32 v11, 0xfffffc62, v10
	v_med3_i32 v11, v11, 0, v90
	v_lshl_add_u32 v133, v11, 2, s69
	v_add_u32_e32 v11, 0xfffffcb2, v10
	v_med3_i32 v11, v11, 0, v90
	v_lshl_add_u32 v134, v11, 2, s69
	v_add_u32_e32 v11, 0xfffffcc2, v10
	v_med3_i32 v11, v11, 0, v90
	v_lshl_add_u32 v135, v11, 2, s69
	v_add_u32_e32 v11, 0xfffffcd2, v10
	v_med3_i32 v11, v11, 0, v90
	v_lshl_add_u32 v136, v11, 2, s69
	v_add_u32_e32 v11, 0xfffffce2, v10
	v_med3_i32 v11, v11, 0, v90
	v_lshl_add_u32 v137, v11, 2, s69
	v_add_u32_e32 v11, 0xfffffd32, v10
	v_med3_i32 v11, v11, 0, v90
	v_lshl_add_u32 v138, v11, 2, s69
	v_add_u32_e32 v11, 0xfffffd42, v10
	v_med3_i32 v11, v11, 0, v90
	v_lshl_add_u32 v139, v11, 2, s69
	v_add_u32_e32 v11, 0xfffffd52, v10
	v_med3_i32 v11, v11, 0, v90
	v_lshl_add_u32 v140, v11, 2, s69
	v_add_u32_e32 v11, 0xfffffd62, v10
	v_med3_i32 v11, v11, 0, v90
	v_lshl_add_u32 v141, v11, 2, s69
	v_add_u32_e32 v11, 0xfffffdb2, v10
	v_med3_i32 v11, v11, 0, v90
	v_lshl_add_u32 v142, v11, 2, s69
	v_add_u32_e32 v11, 0xfffffdc2, v10
	v_med3_i32 v11, v11, 0, v90
	v_lshl_add_u32 v143, v11, 2, s69
	v_add_u32_e32 v11, 0xfffffdd2, v10
	v_med3_i32 v11, v11, 0, v90
	v_lshl_add_u32 v144, v11, 2, s69
	v_add_u32_e32 v11, 0xfffffde2, v10
	v_med3_i32 v11, v11, 0, v90
	v_lshl_add_u32 v145, v11, 2, s69
	v_add_u32_e32 v11, 0xfffffe32, v10
	v_med3_i32 v11, v11, 0, v90
	v_lshl_add_u32 v146, v11, 2, s69
	v_add_u32_e32 v11, 0xfffffe42, v10
	v_med3_i32 v11, v11, 0, v90
	v_lshl_add_u32 v147, v11, 2, s69
	v_add_u32_e32 v11, 0xfffffe52, v10
	v_med3_i32 v11, v11, 0, v90
	v_lshl_add_u32 v148, v11, 2, s69
	v_add_u32_e32 v11, 0xfffffe62, v10
	v_med3_i32 v11, v11, 0, v90
	v_lshl_add_u32 v149, v11, 2, s69
	v_add_u32_e32 v11, 0xfffffeb2, v10
	v_med3_i32 v11, v11, 0, v90
	v_lshl_add_u32 v150, v11, 2, s69
	v_add_u32_e32 v11, 0xfffffec2, v10
	v_med3_i32 v11, v11, 0, v90
	v_lshl_add_u32 v151, v11, 2, s69
	v_add_u32_e32 v11, 0xfffffed2, v10
	v_med3_i32 v11, v11, 0, v90
	v_lshl_add_u32 v152, v11, 2, s69
	v_add_u32_e32 v11, 0xfffffee2, v10
	v_med3_i32 v11, v11, 0, v90
	v_lshl_add_u32 v153, v11, 2, s69
	v_add_u32_e32 v11, 0xffffff32, v10
	v_med3_i32 v11, v11, 0, v90
	v_lshl_add_u32 v154, v11, 2, s69
	v_add_u32_e32 v11, 0xffffff42, v10
	v_med3_i32 v11, v11, 0, v90
	v_lshl_add_u32 v155, v11, 2, s69
	v_add_u32_e32 v11, 0xffffff52, v10
	s_lshl_b32 s1, s75, 8
	v_med3_i32 v11, v11, 0, v90
	s_and_b32 s1, s1, 0x700
	v_and_or_b32 v2, v8, 4, v2
	v_lshl_add_u32 v156, v11, 2, s69
	v_add_u32_e32 v11, 0xffffff62, v10
	v_add_u32_e32 v94, s1, v3
	v_mad_u32_u24 v8, v2, s67, 0
	v_mad_i64_i32 v[2:3], s[0:1], v0, s68, 0
	v_med3_i32 v11, v11, 0, v90
	v_mul_i32_i24_e32 v7, 0xffffffc0, v4
	v_ashrrev_i32_e32 v1, 31, v0
	v_mad_i64_i32 v[2:3], s[0:1], s18, v89, v[2:3]
	v_lshl_add_u32 v157, v11, 2, s69
	v_add_u32_e32 v11, 0xffffffb2, v10
	v_med3_i32 v11, v11, 0, v90
	v_add3_u32 v7, v0, v7, s70
	s_lshl_b64 s[0:1], s[18:19], 22
	v_lshlrev_b64 v[0:1], 11, v[0:1]
	v_lshlrev_b32_e32 v5, 4, v4
	v_lshl_add_u32 v158, v11, 2, s69
	v_subrev_u32_e32 v11, 62, v10
	v_subrev_u32_e32 v10, 46, v10
	v_lshl_add_u64 v[0:1], s[0:1], 0, v[0:1]
	v_mad_u32_u24 v6, v64, s54, 0
	v_lshl_add_u64 v[66:67], s[8:9], 0, v[2:3]
	v_med3_i32 v11, v11, 0, v90
	v_med3_i32 v10, v10, 0, v90
	v_med3_i32 v7, v7, 0, v90
	v_or_b32_e32 v2, v2, v5
	v_lshl_or_b32 v0, v4, 3, v0
	s_mov_b32 s20, 0
	v_lshl_add_u32 v159, v11, 2, s69
	v_lshl_add_u32 v160, v10, 2, s69
	v_lshl_add_u32 v161, v7, 2, s69
	v_lshl_add_u64 v[68:69], s[10:11], 0, v[2:3]
	v_lshl_add_u64 v[70:71], s[12:13], 0, v[0:1]
	v_add_u32_e32 v162, v6, v5
	v_add_u32_e32 v163, v8, v9
	s_waitcnt lgkmcnt(0)
	s_barrier
	ds_write2_b32 v96, v65, v65 offset1:2
	ds_write2_b32 v96, v65, v65 offset0:4 offset1:6
	ds_write2_b32 v96, v65, v65 offset0:8 offset1:10
	ds_write2_b32 v96, v65, v65 offset0:12 offset1:14
	ds_write2_b32 v96, v65, v65 offset0:16 offset1:18
	ds_write2_b32 v96, v65, v65 offset0:20 offset1:22
	ds_write2_b32 v96, v65, v65 offset0:24 offset1:26
	ds_write2_b32 v96, v65, v65 offset0:28 offset1:30
	global_load_dwordx4 v[204:207], v[68:69], off offset:-64
	global_load_dwordx4 v[208:211], v[68:69], off offset:-32
	global_load_dwordx4 v[212:215], v[68:69], off offset:0
	global_load_dwordx4 v[216:219], v[68:69], off offset:32
	global_load_ushort v220, v[66:67], off offset:0
	s_waitcnt vmcnt(0)
	s_branch .Lnsa1_enter
.LBB0_517:
	s_or_b64 exec, exec, s[4:5]
	s_waitcnt lgkmcnt(0)
	v_mul_f32_e32 v25, v4, v47
	v_mul_f32_e32 v27, v5, v47
	v_mul_f32_e32 v24, v1, v47
	v_mul_f32_e32 v26, v2, v47
	v_mul_f32_e32 v31, v7, v47
	v_cndmask_b32_e64 v4, 0, v27, s[2:3]
	v_fma_f32 v1, v1, v47, v25
	v_fma_f32 v2, v2, v47, v27
	ds_bpermute_b32 v4, v97, v4
	v_add_f32_e32 v1, v1, v2
	v_cndmask_b32_e64 v2, v27, v31, s[2:3]
	ds_bpermute_b32 v2, v97, v2
	v_mul_f32_e32 v29, v6, v47
	v_mul_f32_e32 v28, v0, v47
	v_mul_f32_e32 v30, v3, v47
	v_fma_f32 v0, v0, v47, v29
	v_fma_f32 v3, v3, v47, v31
	v_mul_f32_e32 v81, v8, v47
	v_mul_f32_e32 v82, v9, v47
	v_mul_f32_e32 v83, v10, v47
	v_mul_f32_e32 v84, v11, v47
	s_waitcnt lgkmcnt(1)
	v_add_f32_e32 v1, v1, v4
	ds_read2_b32 v[4:5], v96 offset1:2
	ds_read2_b32 v[6:7], v96 offset0:4 offset1:6
	ds_read2_b32 v[8:9], v96 offset0:8 offset1:10
	ds_read2_b32 v[10:11], v96 offset0:12 offset1:14
	v_add_f32_e32 v0, v0, v3
	s_waitcnt lgkmcnt(4)
	v_add_f32_e32 v0, v0, v2
	s_waitcnt lgkmcnt(3)
	v_add_f32_e32 v1, v4, v1
	v_add_f32_e32 v0, v5, v0
	v_cndmask_b32_e64 v2, v31, v82, s[2:3]
	ds_bpermute_b32 v2, v97, v2
	ds_write2_b32 v96, v1, v0 offset1:2
	v_fma_f32 v0, v72, v47, v81
	v_fma_f32 v1, v73, v47, v82
	v_add_f32_e32 v0, v0, v1
	v_cndmask_b32_e64 v1, v82, v84, s[2:3]
	ds_bpermute_b32 v1, v97, v1
	s_waitcnt lgkmcnt(2)
	v_add_f32_e32 v0, v0, v2
	v_fma_f32 v2, v74, v47, v83
	v_fma_f32 v3, v75, v47, v84
	v_add_f32_e32 v2, v2, v3
	v_mul_f32_e32 v86, v13, v47
	s_waitcnt lgkmcnt(0)
	v_add_f32_e32 v1, v2, v1
	v_mul_f32_e32 v85, v12, v47
	v_add_f32_e32 v0, v6, v0
	v_add_f32_e32 v1, v7, v1
	v_cndmask_b32_e64 v2, v84, v86, s[2:3]
	v_mul_f32_e32 v164, v15, v47
	ds_bpermute_b32 v2, v97, v2
	ds_write2_b32 v96, v0, v1 offset0:4 offset1:6
	v_fma_f32 v0, v54, v47, v85
	v_fma_f32 v1, v52, v47, v86
	v_add_f32_e32 v0, v0, v1
	v_cndmask_b32_e64 v1, v86, v164, s[2:3]
	ds_bpermute_b32 v1, v97, v1
	v_mul_f32_e32 v87, v14, v47
	s_waitcnt lgkmcnt(2)
	v_add_f32_e32 v0, v0, v2
	v_fma_f32 v2, v53, v47, v87
	v_fma_f32 v3, v55, v47, v164
	v_add_f32_e32 v2, v2, v3
	v_mul_f32_e32 v166, v61, v47
	s_waitcnt lgkmcnt(0)
	v_add_f32_e32 v1, v2, v1
	v_mul_f32_e32 v165, v60, v47
	v_add_f32_e32 v0, v8, v0
	v_add_f32_e32 v1, v9, v1
	v_cndmask_b32_e64 v2, v164, v166, s[2:3]
	v_mul_f32_e32 v57, v57, v47
	ds_bpermute_b32 v2, v97, v2
	ds_write2_b32 v96, v0, v1 offset0:8 offset1:10
	v_fma_f32 v0, v48, v47, v165
	v_fma_f32 v1, v49, v47, v166
	v_add_f32_e32 v0, v0, v1
	v_cndmask_b32_e64 v1, v166, v57, s[2:3]
	ds_bpermute_b32 v1, v97, v1
	v_mul_f32_e32 v167, v58, v47
	s_waitcnt lgkmcnt(2)
	v_add_f32_e32 v0, v0, v2
	v_fma_f32 v2, v50, v47, v167
	v_fma_f32 v3, v51, v47, v57
	v_add_f32_e32 v2, v2, v3
	s_waitcnt lgkmcnt(0)
	v_add_f32_e32 v1, v2, v1
	v_mul_f32_e32 v62, v62, v47
	v_add_f32_e32 v0, v10, v0
	v_add_f32_e32 v1, v11, v1
	ds_write2_b32 v96, v0, v1 offset0:12 offset1:14
	v_cndmask_b32_e64 v0, v57, v62, s[2:3]
	ds_bpermute_b32 v2, v97, v0
	v_mul_f32_e32 v168, v59, v47
	v_fma_f32 v3, v38, v47, v168
	v_fma_f32 v4, v36, v47, v62
	v_mul_f32_e32 v169, v76, v47
	ds_read2_b32 v[0:1], v96 offset0:16 offset1:18
	v_add_f32_e32 v3, v3, v4
	s_waitcnt lgkmcnt(1)
	v_add_f32_e32 v2, v3, v2
	v_cndmask_b32_e64 v3, v62, v169, s[2:3]
	ds_bpermute_b32 v3, v97, v3
	v_mul_f32_e32 v63, v63, v47
	s_waitcnt lgkmcnt(1)
	v_add_f32_e32 v0, v0, v2
	v_fma_f32 v2, v39, v47, v63
	v_fma_f32 v4, v56, v47, v169
	v_add_f32_e32 v2, v2, v4
	s_waitcnt lgkmcnt(0)
	v_add_f32_e32 v2, v2, v3
	v_mul_f32_e32 v171, v78, v47
	v_add_f32_e32 v1, v1, v2
	ds_write2_b32 v96, v0, v1 offset0:16 offset1:18
	v_cndmask_b32_e64 v0, v169, v171, s[2:3]
	ds_bpermute_b32 v2, v97, v0
	v_mul_f32_e32 v170, v77, v47
	v_fma_f32 v3, v32, v47, v170
	v_fma_f32 v4, v34, v47, v171
	v_mul_f32_e32 v80, v80, v47
	ds_read2_b32 v[0:1], v96 offset0:20 offset1:22
	v_add_f32_e32 v3, v3, v4
	s_waitcnt lgkmcnt(1)
	v_add_f32_e32 v2, v3, v2
	v_cndmask_b32_e64 v3, v171, v80, s[2:3]
	ds_bpermute_b32 v3, v97, v3
	v_mul_f32_e32 v172, v79, v47
	s_waitcnt lgkmcnt(1)
	v_add_f32_e32 v0, v0, v2
	v_fma_f32 v2, v42, v47, v172
	v_fma_f32 v4, v43, v47, v80
	v_add_f32_e32 v2, v2, v4
	s_waitcnt lgkmcnt(0)
	v_add_f32_e32 v2, v2, v3
	v_mul_f32_e32 v174, v20, v47
	v_add_f32_e32 v1, v1, v2
	ds_write2_b32 v96, v0, v1 offset0:20 offset1:22
	v_cndmask_b32_e64 v0, v80, v174, s[2:3]
	ds_bpermute_b32 v2, v97, v0
	v_mul_f32_e32 v173, v22, v47
	v_fma_f32 v3, v33, v47, v173
	v_fma_f32 v4, v35, v47, v174
	v_mul_f32_e32 v176, v17, v47
	ds_read2_b32 v[0:1], v96 offset0:24 offset1:26
	v_add_f32_e32 v3, v3, v4
	s_waitcnt lgkmcnt(1)
	v_add_f32_e32 v2, v3, v2
	v_cndmask_b32_e64 v3, v174, v176, s[2:3]
	ds_bpermute_b32 v3, v97, v3
	v_mul_f32_e32 v175, v16, v47
	s_waitcnt lgkmcnt(1)
	v_add_f32_e32 v0, v0, v2
	v_fma_f32 v2, v40, v47, v175
	v_fma_f32 v4, v44, v47, v176
	v_add_f32_e32 v2, v2, v4
	s_waitcnt lgkmcnt(0)
	v_add_f32_e32 v2, v2, v3
	v_mul_f32_e32 v178, v19, v47
	v_add_f32_e32 v1, v1, v2
	ds_write2_b32 v96, v0, v1 offset0:24 offset1:26
	v_cndmask_b32_e64 v0, v176, v178, s[2:3]
	ds_bpermute_b32 v2, v97, v0
	v_mul_f32_e32 v177, v18, v47
	v_fma_f32 v3, v37, v47, v177
	v_fma_f32 v4, v41, v47, v178
	v_mul_f32_e32 v180, v21, v47
	ds_read2_b32 v[0:1], v96 offset0:28 offset1:30
	v_add_f32_e32 v3, v3, v4
	s_waitcnt lgkmcnt(1)
	v_add_f32_e32 v2, v3, v2
	v_cndmask_b32_e64 v3, v178, v180, s[2:3]
	ds_bpermute_b32 v3, v97, v3
	v_mul_f32_e32 v179, v23, v47
	s_waitcnt lgkmcnt(1)
	v_add_f32_e32 v0, v0, v2
	v_fma_f32 v2, v45, v47, v179
	v_fma_f32 v4, v46, v47, v180
	v_add_f32_e32 v2, v2, v4
	s_waitcnt lgkmcnt(0)
	v_add_f32_e32 v2, v2, v3
	v_add_f32_e32 v1, v1, v2
	ds_write2_b32 v96, v0, v1 offset0:28 offset1:30
	v_cvt_pk_bf16_f32 v16, v24, v25
	v_cvt_pk_bf16_f32 v17, v26, v27
	v_cvt_pk_bf16_f32 v18, v28, v29
	v_cvt_pk_bf16_f32 v19, v30, v31
	ds_read_b64_tr_b16 v[0:1], v163 offset:18432
	ds_read_b64_tr_b16 v[2:3], v163 offset:19968
	ds_read_b64_tr_b16 v[22:23], v163 offset:20032
	ds_read_b64_tr_b16 v[20:21], v163 offset:18496
	s_waitcnt lgkmcnt(2)
	v_mfma_f32_32x32x16_bf16 v[0:15], v[0:3], v[16:19], 0
	v_mul_f32_e32 v58, v72, v47
	v_mul_f32_e32 v59, v73, v47
	v_mul_f32_e32 v60, v74, v47
	v_mul_f32_e32 v61, v75, v47
	v_cvt_pk_bf16_f32 v58, v58, v81
	v_cvt_pk_bf16_f32 v59, v59, v82
	v_cvt_pk_bf16_f32 v60, v60, v83
	s_waitcnt lgkmcnt(0)
	v_mfma_f32_32x32x16_bf16 v[16:31], v[20:23], v[16:19], 0
	v_cvt_pk_bf16_f32 v61, v61, v84
	ds_read_b64_tr_b16 v[72:73], v163 offset:21504
	ds_read_b64_tr_b16 v[74:75], v163 offset:23040
	ds_read_b64_tr_b16 v[78:79], v163 offset:23104
	ds_read_b64_tr_b16 v[76:77], v163 offset:21568
	v_mul_f32_e32 v54, v54, v47
	v_mul_f32_e32 v55, v55, v47
	v_mul_f32_e32 v48, v48, v47
	v_mul_f32_e32 v49, v49, v47
	v_mul_f32_e32 v50, v50, v47
	s_waitcnt lgkmcnt(2)
	v_mfma_f32_32x32x16_bf16 v[0:15], v[72:75], v[58:61], v[0:15]
	v_mul_f32_e32 v72, v52, v47
	v_mul_f32_e32 v73, v53, v47
	v_cvt_pk_bf16_f32 v52, v54, v85
	v_cvt_pk_bf16_f32 v53, v72, v86
	v_cvt_pk_bf16_f32 v54, v73, v87
	v_cvt_pk_bf16_f32 v55, v55, v164
	v_mul_f32_e32 v51, v51, v47
	s_waitcnt lgkmcnt(0)
	v_mfma_f32_32x32x16_bf16 v[16:31], v[76:79], v[58:61], v[16:31]
	ds_read_b64_tr_b16 v[58:59], v163 offset:24576
	ds_read_b64_tr_b16 v[60:61], v163 offset:26112
	ds_read_b64_tr_b16 v[74:75], v163 offset:26176
	ds_read_b64_tr_b16 v[72:73], v163 offset:24640
	v_cvt_pk_bf16_f32 v48, v48, v165
	v_cvt_pk_bf16_f32 v49, v49, v166
	v_cvt_pk_bf16_f32 v50, v50, v167
	v_cvt_pk_bf16_f32 v51, v51, v57
	v_mul_f32_e32 v38, v38, v47
	v_mul_f32_e32 v36, v36, v47
	s_waitcnt lgkmcnt(2)
	v_mfma_f32_32x32x16_bf16 v[0:15], v[58:61], v[52:55], v[0:15]
	v_mul_f32_e32 v39, v39, v47
	v_mul_f32_e32 v32, v32, v47
	v_mul_f32_e32 v34, v34, v47
	v_mul_f32_e32 v41, v41, v47
	s_addk_i32 s20, 0x210
	v_lshl_add_u64 v[68:69], v[68:69], 0, s[14:15]
	s_cmpk_eq_i32 s20, 0x18c0
	s_waitcnt lgkmcnt(0)
	v_mfma_f32_32x32x16_bf16 v[16:31], v[72:75], v[52:55], v[16:31]
	ds_read_b64_tr_b16 v[52:53], v163 offset:27648
	ds_read_b64_tr_b16 v[54:55], v163 offset:29184
	ds_read_b64_tr_b16 v[60:61], v163 offset:29248
	ds_read_b64_tr_b16 v[58:59], v163 offset:27712
	s_waitcnt lgkmcnt(2)
	v_mfma_f32_32x32x16_bf16 v[0:15], v[52:55], v[48:51], v[0:15]
	v_mul_f32_e32 v52, v56, v47
	s_waitcnt lgkmcnt(0)
	v_mfma_f32_32x32x16_bf16 v[16:31], v[58:61], v[48:51], v[16:31]
	v_cvt_pk_bf16_f32 v48, v38, v168
	v_cvt_pk_bf16_f32 v49, v36, v62
	v_cvt_pk_bf16_f32 v50, v39, v63
	v_cvt_pk_bf16_f32 v51, v52, v169
	ds_read_b64_tr_b16 v[52:53], v163 offset:30720
	ds_read_b64_tr_b16 v[54:55], v163 offset:32256
	ds_read_b64_tr_b16 v[58:59], v163 offset:32320
	ds_read_b64_tr_b16 v[56:57], v163 offset:30784
	v_mul_f32_e32 v36, v42, v47
	v_mul_f32_e32 v38, v43, v47
	s_waitcnt lgkmcnt(2)
	v_mfma_f32_32x32x16_bf16 v[0:15], v[52:55], v[48:51], v[0:15]
	v_mul_f32_e32 v42, v45, v47
	v_mul_f32_e32 v43, v46, v47
	s_waitcnt lgkmcnt(0)
	v_mfma_f32_32x32x16_bf16 v[16:31], v[56:59], v[48:51], v[16:31]
	v_cvt_pk_bf16_f32 v48, v32, v170
	v_cvt_pk_bf16_f32 v49, v34, v171
	v_cvt_pk_bf16_f32 v50, v36, v172
	v_cvt_pk_bf16_f32 v51, v38, v80
	ds_read_b64_tr_b16 v[52:53], v163 offset:33792
	ds_read_b64_tr_b16 v[54:55], v163 offset:35328
	ds_read_b64_tr_b16 v[58:59], v163 offset:35392
	ds_read_b64_tr_b16 v[56:57], v163 offset:33856
	v_mul_f32_e32 v32, v33, v47
	v_mul_f32_e32 v33, v35, v47
	v_mul_f32_e32 v34, v40, v47
	v_mul_f32_e32 v35, v44, v47
	v_mul_f32_e32 v40, v37, v47
	s_waitcnt lgkmcnt(2)
	v_mfma_f32_32x32x16_bf16 v[0:15], v[52:55], v[48:51], v[0:15]
	v_cvt_pk_bf16_f32 v32, v32, v173
	v_cvt_pk_bf16_f32 v33, v33, v174
	v_cvt_pk_bf16_f32 v34, v34, v175
	v_cvt_pk_bf16_f32 v35, v35, v176
	s_waitcnt lgkmcnt(0)
	v_mfma_f32_32x32x16_bf16 v[16:31], v[56:59], v[48:51], v[16:31]
	ds_read_b64_tr_b16 v[48:49], v163 offset:36864
	ds_read_b64_tr_b16 v[50:51], v163 offset:38400
	ds_read_b64_tr_b16 v[38:39], v163 offset:38464
	ds_read_b64_tr_b16 v[36:37], v163 offset:36928
	v_cvt_pk_bf16_f32 v40, v40, v177
	v_cvt_pk_bf16_f32 v41, v41, v178
	v_cvt_pk_bf16_f32 v42, v42, v179
	v_cvt_pk_bf16_f32 v43, v43, v180
	s_nop 0
	s_waitcnt lgkmcnt(2)
	v_mfma_f32_32x32x16_bf16 v[0:15], v[48:51], v[32:35], v[0:15]
	v_lshl_add_u64 v[66:67], v[66:67], 0, 6
	s_waitcnt lgkmcnt(0)
	v_mfma_f32_32x32x16_bf16 v[16:31], v[36:39], v[32:35], v[16:31]
	ds_read_b64_tr_b16 v[32:33], v163 offset:39936
	ds_read_b64_tr_b16 v[34:35], v163 offset:41472
	ds_read_b64_tr_b16 v[38:39], v163 offset:41536
	ds_read_b64_tr_b16 v[36:37], v163 offset:40000
	s_waitcnt lgkmcnt(2)
	v_mfma_f32_32x32x16_bf16 v[0:15], v[32:35], v[40:43], v[0:15]
	s_nop 0
	v_lshlrev_b32_e32 v32, 16, v221
	v_mul_f32_e32 v32, 0xbfb8aa3b, v32
	v_exp_f32_e32 v32, v32
	s_waitcnt lgkmcnt(0)
	v_mfma_f32_32x32x16_bf16 v[16:31], v[36:39], v[40:43], v[16:31]
	v_add_f32_e32 v32, 1.0, v32
	v_div_scale_f32 v33, s[0:1], v32, v32, 1.0
	v_rcp_f32_e32 v34, v33
	s_nop 0
	v_fma_f32 v35, -v33, v34, 1.0
	v_fmac_f32_e32 v34, v35, v34
	v_div_scale_f32 v35, vcc, 1.0, v32, 1.0
	v_mul_f32_e32 v36, v35, v34
	v_fma_f32 v37, -v33, v36, v35
	v_fmac_f32_e32 v36, v37, v34
	v_fma_f32 v33, -v33, v36, v35
	v_div_fmas_f32 v33, v33, v34, v36
	v_div_fixup_f32 v32, v33, v32, 1.0
	v_mul_f32_e32 v0, v0, v32
	v_mul_f32_e32 v1, v1, v32
	v_mul_f32_e32 v2, v2, v32
	v_mul_f32_e32 v3, v3, v32
	v_cvt_pk_bf16_f32 v0, v0, v1
	v_cvt_pk_bf16_f32 v1, v2, v3
	v_mul_f32_e32 v16, v16, v32
	v_mul_f32_e32 v17, v17, v32
	v_mul_f32_e32 v18, v18, v32
	v_mul_f32_e32 v19, v19, v32
	v_mul_f32_e32 v4, v4, v32
	v_mul_f32_e32 v5, v5, v32
	v_mul_f32_e32 v6, v6, v32
	v_mul_f32_e32 v7, v7, v32
	v_cvt_pk_bf16_f32 v2, v16, v17
	v_cvt_pk_bf16_f32 v3, v18, v19
	global_store_dwordx2 v[70:71], v[0:1], off offset:-64
	global_store_dwordx2 v[70:71], v[2:3], off
	v_cvt_pk_bf16_f32 v0, v4, v5
	v_cvt_pk_bf16_f32 v1, v6, v7
	v_mul_f32_e32 v20, v20, v32
	v_mul_f32_e32 v21, v21, v32
	v_mul_f32_e32 v22, v22, v32
	v_mul_f32_e32 v23, v23, v32
	v_mul_f32_e32 v8, v8, v32
	v_mul_f32_e32 v9, v9, v32
	v_mul_f32_e32 v10, v10, v32
	v_mul_f32_e32 v11, v11, v32
	v_cvt_pk_bf16_f32 v2, v20, v21
	v_cvt_pk_bf16_f32 v3, v22, v23
	global_store_dwordx2 v[70:71], v[0:1], off offset:-48
	global_store_dwordx2 v[70:71], v[2:3], off offset:16
	v_cvt_pk_bf16_f32 v0, v8, v9
	v_cvt_pk_bf16_f32 v1, v10, v11
	v_mul_f32_e32 v24, v24, v32
	v_mul_f32_e32 v25, v25, v32
	v_mul_f32_e32 v26, v26, v32
	v_mul_f32_e32 v27, v27, v32
	v_mul_f32_e32 v12, v12, v32
	v_mul_f32_e32 v13, v13, v32
	v_mul_f32_e32 v14, v14, v32
	v_mul_f32_e32 v15, v15, v32
	v_cvt_pk_bf16_f32 v2, v24, v25
	v_cvt_pk_bf16_f32 v3, v26, v27
	global_store_dwordx2 v[70:71], v[0:1], off offset:-32
	global_store_dwordx2 v[70:71], v[2:3], off offset:32
	v_cvt_pk_bf16_f32 v0, v12, v13
	v_cvt_pk_bf16_f32 v1, v14, v15
	v_mul_f32_e32 v28, v28, v32
	v_mul_f32_e32 v29, v29, v32
	v_mul_f32_e32 v30, v30, v32
	v_mul_f32_e32 v31, v31, v32
	v_cvt_pk_bf16_f32 v2, v28, v29
	v_cvt_pk_bf16_f32 v3, v30, v31
	global_store_dwordx2 v[70:71], v[0:1], off offset:-16
	global_store_dwordx2 v[70:71], v[2:3], off offset:48
	v_lshl_add_u64 v[70:71], v[70:71], 0, s[14:15]
	s_cbranch_scc1 .LBB0_544

.Lnsa1_enter:
	v_mov_b32_e32 v221, v220
	v_mov_b64_e32 v[0:1], v[204:205]
	v_mov_b64_e32 v[2:3], v[206:207]
	v_mov_b64_e32 v[72:73], v[208:209]
	v_mov_b64_e32 v[74:75], v[210:211]
	ds_read_b128 v[4:7], v162
	ds_read_b128 v[76:79], v162 offset:32
	v_readfirstlane_b32 s0, v94
	s_mov_b64 s[4:5], -1
	s_cmpk_lt_i32 s0, 0x28f
	s_waitcnt lgkmcnt(1)
	v_mfma_f32_32x32x16_bf16 v[48:63], v[4:7], v[0:3], 0
	ds_read_b128 v[4:7], v162 offset:4608
	ds_read_b128 v[80:83], v162 offset:4640
	s_waitcnt lgkmcnt(1)
	v_mfma_f32_32x32x16_bf16 v[32:47], v[4:7], v[0:3], 0
	ds_read_b128 v[4:7], v162 offset:9216
	ds_read_b128 v[84:87], v162 offset:9248
	s_waitcnt lgkmcnt(1)
	v_mfma_f32_32x32x16_bf16 v[16:31], v[4:7], v[0:3], 0
	ds_read_b128 v[4:7], v162 offset:13824
	ds_read_b128 v[164:167], v162 offset:13856
	v_mov_b64_e32 v[168:169], v[216:217]
	v_mov_b64_e32 v[170:171], v[218:219]
	v_mfma_f32_32x32x16_bf16 v[48:63], v[76:79], v[72:75], v[48:63]
	v_mov_b64_e32 v[76:77], v[212:213]
	v_mov_b64_e32 v[78:79], v[214:215]
	global_load_dwordx4 v[204:207], v[68:69], off offset:64
	global_load_dwordx4 v[208:211], v[68:69], off offset:96
	global_load_dwordx4 v[212:215], v[68:69], off offset:128
	global_load_dwordx4 v[216:219], v[68:69], off offset:160
	global_load_ushort v220, v[66:67], off offset:6
	s_waitcnt lgkmcnt(1)
	v_mfma_f32_32x32x16_bf16 v[0:15], v[4:7], v[0:3], 0
	v_mfma_f32_32x32x16_bf16 v[32:47], v[80:83], v[72:75], v[32:47]
	v_mfma_f32_32x32x16_bf16 v[16:31], v[84:87], v[72:75], v[16:31]
	s_waitcnt lgkmcnt(0)
	v_mfma_f32_32x32x16_bf16 v[0:15], v[164:167], v[72:75], v[0:15]
	ds_read_b128 v[72:75], v162 offset:64
	ds_read_b128 v[80:83], v162 offset:96
	s_waitcnt lgkmcnt(1)
	v_mfma_f32_32x32x16_bf16 v[48:63], v[72:75], v[76:79], v[48:63]
	ds_read_b128 v[72:75], v162 offset:4672
	ds_read_b128 v[84:87], v162 offset:4704
	s_waitcnt lgkmcnt(1)
	v_mfma_f32_32x32x16_bf16 v[32:47], v[72:75], v[76:79], v[32:47]
	ds_read_b128 v[72:75], v162 offset:9280
	ds_read_b128 v[164:167], v162 offset:9312
	s_waitcnt lgkmcnt(1)
	v_mfma_f32_32x32x16_bf16 v[16:31], v[72:75], v[76:79], v[16:31]
	ds_read_b128 v[72:75], v162 offset:13888
	ds_read_b128 v[172:175], v162 offset:13920
	s_waitcnt lgkmcnt(1)
	v_mfma_f32_32x32x16_bf16 v[0:15], v[72:75], v[76:79], v[0:15]
	v_mfma_f32_32x32x16_bf16 v[48:63], v[80:83], v[168:171], v[48:63]
	v_mfma_f32_32x32x16_bf16 v[32:47], v[84:87], v[168:171], v[32:47]
	v_mfma_f32_32x32x16_bf16 v[16:31], v[164:167], v[168:171], v[16:31]
	s_waitcnt lgkmcnt(0)
	v_mfma_f32_32x32x16_bf16 v[0:15], v[172:175], v[168:171], v[0:15]
	s_cbranch_scc1 .LBB0_520
	s_add_i32 s1, s20, 0
	v_mov_b32_e32 v72, s1
	ds_read_b32 v82, v72 offset:43524
	s_mov_b64 s[4:5], 0
	s_waitcnt lgkmcnt(0)
	s_nop 1
	v_pk_add_f32 v[78:79], v[48:49], v[82:83] op_sel_hi:[1,0]
	v_pk_add_f32 v[76:77], v[50:51], v[82:83] op_sel_hi:[1,0]
	v_max3_f32 v80, v78, s71, v79
	v_pk_add_f32 v[72:73], v[52:53], v[82:83] op_sel_hi:[1,0]
	v_max3_f32 v80, v80, v76, v77
	v_pk_add_f32 v[74:75], v[54:55], v[82:83] op_sel_hi:[1,0]
	v_max3_f32 v80, v80, v72, v73
	v_pk_add_f32 v[84:85], v[56:57], v[82:83] op_sel_hi:[1,0]
	v_max3_f32 v80, v80, v74, v75
	v_max3_f32 v80, v80, v84, v85
	v_pk_add_f32 v[86:87], v[58:59], v[82:83] op_sel_hi:[1,0]
	s_nop 0
	v_max3_f32 v83, v80, v86, v87
	v_pk_add_f32 v[80:81], v[60:61], v[82:83] op_sel_hi:[1,0]
	s_nop 0
	v_max3_f32 v164, v83, v80, v81
	v_pk_add_f32 v[82:83], v[62:63], v[82:83] op_sel_hi:[1,0]
	s_nop 0
	v_max3_f32 v164, v164, v82, v83

.LBB0_544:
	s_waitcnt vmcnt(0)
	v_ashrrev_i32_e32 v1, 6, v94
	v_cmp_lt_i32_e32 vcc, 15, v1
	s_barrier
	s_and_saveexec_b64 s[0:1], vcc
	s_xor_b64 s[20:21], exec, s[0:1]
	s_cbranch_execz .LBB0_551
	v_lshlrev_b32_e64 v0, v1, 1
	v_add_u32_e32 v1, -1, v1
	v_lshlrev_b32_e64 v2, v1, 1
	v_bfm_b32 v1, v1, 0
	v_or3_b32 v0, v0, v2, 1
	v_and_b32_e32 v1, -2, v1
	v_add_u32_e32 v2, s74, v95
	s_mov_b32 s0, 0
